# attention loops (diff + MLA): counted lgkmcnt waits in the PV MFMA block (each MFMA waits only for the transposed reads it consumes; reads return in order)
# speedup vs baseline: 1.0047x; 1.0031x over previous
; template <int D0> __device__ __forceinline__ void pv_one(f32x16& od, int vb, bf16x8 pa0, bf16x8 pa1, bf16x8 pa2, bf16x8 pa3) {
;     const s16x4 l0 = tr_read<v_rd_off(D0, 0, 0)>(vb), h0 = tr_read<v_rd_off(D0, 0, 1)>(vb), l1 = tr_read<v_rd_off(D0, 1, 0)>(vb), h1 = tr_read<v_rd_off(D0, 1, 1)>(vb);
;     const s16x4 l2 = tr_read<v_rd_off(D0, 2, 0)>(vb), h2 = tr_read<v_rd_off(D0, 2, 1)>(vb), l3 = tr_read<v_rd_off(D0, 3, 0)>(vb), h3 = tr_read<v_rd_off(D0, 3, 1)>(vb);
;     asm volatile("s_waitcnt lgkmcnt(0)" ::: "memory"); SBAR();
;     ...
;     od = __builtin_amdgcn_mfma_f32_32x32x16_bf16(pa0, PK(l0, h0), od, 0, 0, 0);
;     od = __builtin_amdgcn_mfma_f32_32x32x16_bf16(pa1, PK(l1, h1), od, 0, 0, 0);
;     od = __builtin_amdgcn_mfma_f32_32x32x16_bf16(pa2, PK(l2, h2), od, 0, 0, 0);
;     od = __builtin_amdgcn_mfma_f32_32x32x16_bf16(pa3, PK(l3, h3), od, 0, 0, 0);
;     ...
; }
; __device__ __forceinline__ void pv_d0(f32x16* o, int vb, bf16x8 pa0, bf16x8 pa1, bf16x8 pa2, bf16x8 pa3) {
;     pv_one<0>(o[0], vb, pa0, pa1, pa2, pa3); pv_one<1>(o[1], vb, pa0, pa1, pa2, pa3); pv_one<2>(o[2], vb, pa0, pa1, pa2, pa3); pv_one<3>(o[3], vb, pa0, pa1, pa2, pa3);
; }
; __device__ __forceinline__ void partialSM(f32x16& p0, f32x16& p1, float& m_reg, float& mn, float& alpha, const float C, const float thr) {
;     float pmax = p0[0];
; #pragma unroll
;     for (int r = 1; r < 16; ++r) pmax = fmaxf(pmax, p0[r]);
; #pragma unroll
;     for (int r = 0; r < 16; ++r) pmax = fmaxf(pmax, p1[r]);
;     { auto rr = __builtin_amdgcn_permlane32_swap(__float_as_uint(pmax), __float_as_uint(pmax), false, false);
;       pmax = fmaxf(__uint_as_float(rr[0]), __uint_as_float(rr[1])); }
;     if (__builtin_expect(__all(pmax - m_reg <= thr), 1)) { mn = m_reg; alpha = 1.f; }
;     else { mn = fmaxf(m_reg, pmax); alpha = __builtin_amdgcn_exp2f((m_reg - mn) * C); m_reg = mn; }
;     const float mnC = -mn * C;
; #pragma unroll
;     for (int r = 0; r < 16; ++r) p0[r] = fmaf(p0[r], C, mnC);
; #pragma unroll
;     for (int r = 0; r < 16; ++r) p1[r] = fmaf(p1[r], C, mnC);
; #pragma unroll
;     for (int r = 0; r < 16; ++r) p0[r] = __builtin_amdgcn_exp2f(p0[r]);
; }
; __device__ __forceinline__ void finishSM(f32x16& p0, f32x16& p1, float alpha, float& l_reg, bf16x8& pa0, bf16x8& pa1, bf16x8& pa2, bf16x8& pa3) {
; #pragma unroll
;     for (int r = 0; r < 16; ++r) p1[r] = __builtin_amdgcn_exp2f(p1[r]);
;     float ps = 0;
.LBB0_171:
	s_add_i32 s37, s52, -3
	ds_read_b128 v[64:67], v186 offset:40960
	ds_read_b128 v[68:71], v186 offset:45056
	v_exp_f32_e32 v143, v138
	v_add_f32_e32 v138, 0, v217
	v_add_f32_e32 v138, v219, v138
	s_waitcnt lgkmcnt(1)
	v_mfma_f32_32x32x16_bf16 v[80:95], v[64:67], v[110:113], 0
	v_add_f32_e32 v138, v208, v138
	v_add_f32_e32 v138, v218, v138
	v_add_f32_e32 v138, v153, v138
	ds_read_b128 v[204:207], v188 offset:40960
	ds_read_b128 v[220:223], v188 offset:45056
	v_add_f32_e32 v138, v216, v138
	v_add_f32_e32 v138, v152, v138
	v_add_f32_e32 v138, v202, v138
	s_waitcnt lgkmcnt(2)
	v_mfma_f32_32x32x16_bf16 v[64:79], v[68:71], v[110:113], 0
	v_add_f32_e32 v138, v149, v138
	v_add_f32_e32 v138, v151, v138
	v_add_f32_e32 v138, v147, v138
	v_add_f32_e32 v138, v150, v138
	v_add_f32_e32 v138, v145, v138
	v_exp_f32_e32 v191, v139
	v_add_f32_e32 v138, v148, v138
	s_waitcnt lgkmcnt(1)
	v_mfma_f32_32x32x16_bf16 v[80:95], v[204:207], v[106:109], v[80:95]
	v_exp_f32_e32 v136, v136
	v_add_f32_e32 v138, v144, v138
	v_exp_f32_e32 v137, v137
	v_add_f32_e32 v138, v146, v138
	v_exp_f32_e32 v130, v130
	v_add_f32_e32 v138, v143, v138
	v_exp_f32_e32 v131, v131
	s_waitcnt lgkmcnt(0)
	v_mfma_f32_32x32x16_bf16 v[64:79], v[220:223], v[106:109], v[64:79]
	ds_read_b128 v[204:207], v190 offset:40960
	ds_read_b128 v[220:223], v190 offset:45056
	v_add_f32_e32 v138, v191, v138
	v_exp_f32_e32 v128, v128
	v_add_f32_e32 v138, v136, v138
	v_exp_f32_e32 v129, v129
	v_add_f32_e32 v138, v137, v138
	v_exp_f32_e32 v126, v126
	s_waitcnt lgkmcnt(1)
	v_mfma_f32_32x32x16_bf16 v[80:95], v[204:207], v[102:105], v[80:95]
	v_add_f32_e32 v138, v130, v138
	v_exp_f32_e32 v127, v127
	v_add_f32_e32 v138, v131, v138
	v_exp_f32_e32 v200, v140
	v_add_f32_e32 v138, v128, v138
	v_exp_f32_e32 v210, v141
	v_add_f32_e32 v138, v129, v138
	s_waitcnt lgkmcnt(0)
	v_mfma_f32_32x32x16_bf16 v[64:79], v[220:223], v[102:105], v[64:79]
	ds_read_b128 v[204:207], v192 offset:40960
	ds_read_b128 v[220:223], v192 offset:45056
	v_exp_f32_e32 v134, v134
	v_add_f32_e32 v138, v126, v138
	v_exp_f32_e32 v135, v135
	v_add_f32_e32 v138, v127, v138
	v_exp_f32_e32 v132, v132
	v_add_f32_e32 v138, v200, v138
	s_waitcnt lgkmcnt(1)
	v_mfma_f32_32x32x16_bf16 v[80:95], v[204:207], v[98:101], v[80:95]
	v_exp_f32_e32 v133, v133
	v_add_f32_e32 v138, v210, v138
	v_add_f32_e32 v138, v134, v138
	v_add_f32_e32 v138, v135, v138
	v_add_f32_e32 v138, v132, v138
	v_add_f32_e32 v196, v133, v138
	v_mov_b32_e32 v198, v196
	s_waitcnt lgkmcnt(0)
	v_mfma_f32_32x32x16_bf16 v[64:79], v[220:223], v[98:101], v[64:79]
	ds_read_b64_tr_b16 v[220:221], v180 offset:0x1000
	ds_read_b64_tr_b16 v[222:223], v180 offset:0x1800
	ds_read_b64_tr_b16 v[224:225], v180 offset:0x2000
	ds_read_b64_tr_b16 v[226:227], v180 offset:0x2800
	ds_read_b64_tr_b16 v[228:229], v180 offset:0x3000
	ds_read_b64_tr_b16 v[230:231], v180 offset:0x3800
	v_cvt_pk_bf16_f32 v138, v217, v219
	v_cvt_pk_bf16_f32 v139, v208, v218
	v_cvt_pk_bf16_f32 v140, v153, v216
	ds_read_b64_tr_b16 v[216:217], v180 offset:0
	ds_read_b64_tr_b16 v[218:219], v180 offset:0x800
	v_permlane32_swap_b32_e32 v196, v198
	v_cvt_pk_bf16_f32 v141, v152, v202
	v_permlane32_swap_b32_e32 v138, v140
	v_cvt_pk_bf16_f32 v204, v149, v151
	v_cvt_pk_bf16_f32 v205, v147, v150
	v_cvt_pk_bf16_f32 v206, v145, v148
	v_cvt_pk_bf16_f32 v207, v144, v146
	v_cvt_pk_bf16_f32 v144, v143, v191
	v_cvt_pk_bf16_f32 v145, v136, v137
	v_cvt_pk_bf16_f32 v146, v130, v131
	v_cvt_pk_bf16_f32 v147, v128, v129
	v_cvt_pk_bf16_f32 v148, v126, v127
	v_cvt_pk_bf16_f32 v149, v200, v210
	v_cvt_pk_bf16_f32 v150, v134, v135
	v_cvt_pk_bf16_f32 v151, v132, v133
	v_permlane32_swap_b32_e32 v139, v141
	v_permlane32_swap_b32_e32 v204, v206
	v_permlane32_swap_b32_e32 v205, v207
	v_permlane32_swap_b32_e32 v144, v146
	v_permlane32_swap_b32_e32 v145, v147
	v_permlane32_swap_b32_e32 v148, v150
	v_permlane32_swap_b32_e32 v149, v151
	s_cmp_lt_u32 s37, 30
	s_cselect_b32 s14, 0, 0xffffffe0
	s_cselect_b32 s15, s18, s86
	s_add_i32 s14, s14, s52
	s_lshl_b32 s14, s14, 6
	s_add_i32 s14, s14, s15
	s_sub_i32 s14, s14, 64
	s_ashr_i32 s15, s14, 31
	v_lshl_add_u64 v[126:127], s[14:15], 0, v[164:165]
	v_lshl_add_u64 v[130:131], v[168:169], 0, s[14:15]
	v_mad_u64_u32 v[128:129], s[38:39], v126, s9, v[170:171]
	v_mad_u64_u32 v[132:133], s[38:39], v130, s9, v[170:171]
	v_mad_i32_i24 v129, v127, s9, v129
	v_mad_i32_i24 v133, v131, s9, v133
	v_mad_i64_i32 v[134:135], s[14:15], s14, v195, v[166:167]
	global_load_dwordx4 v[126:129], v[128:129], off
	s_nop 0
	global_load_dwordx4 v[130:133], v[132:133], off
	s_nop 0
	global_load_dwordx4 v[134:137], v[134:135], off
	s_waitcnt lgkmcnt(0)
	s_nop 0
	v_mfma_f32_32x32x16_bf16 v[48:63], v[138:141], v[216:219], v[48:63]
	ds_read_b64_tr_b16 v[216:217], v180 offset:0x200
	ds_read_b64_tr_b16 v[218:219], v180 offset:0xa00
	v_max_f32_e32 v238, v81, v81
	v_max_f32_e32 v239, v80, v80
	v_max_f32_e32 v238, v239, v238
	v_max3_f32 v238, v238, v82, v83
	v_max3_f32 v238, v238, v84, v85
	v_max3_f32 v238, v238, v86, v87
	v_mfma_f32_32x32x16_bf16 v[48:63], v[204:207], v[220:223], v[48:63]
	ds_read_b64_tr_b16 v[220:221], v180 offset:0x1200
	ds_read_b64_tr_b16 v[222:223], v180 offset:0x1a00
	v_max3_f32 v238, v238, v88, v89
	v_max3_f32 v238, v238, v90, v91
	v_max3_f32 v238, v238, v92, v93
	v_max3_f32 v238, v238, v94, v95
	v_max3_f32 v238, v238, v64, v65
	v_max3_f32 v238, v238, v66, v67
	v_mfma_f32_32x32x16_bf16 v[48:63], v[144:147], v[224:227], v[48:63]
	ds_read_b64_tr_b16 v[224:225], v180 offset:0x2200
	ds_read_b64_tr_b16 v[226:227], v180 offset:0x2a00
	v_max3_f32 v238, v238, v68, v69
	v_max3_f32 v238, v238, v70, v71
	v_max3_f32 v238, v238, v72, v73
	v_max3_f32 v238, v238, v74, v75
	v_max3_f32 v238, v238, v76, v77
	v_max3_f32 v238, v238, v78, v79
	v_mfma_f32_32x32x16_bf16 v[48:63], v[148:151], v[228:231], v[48:63]
	ds_read_b64_tr_b16 v[228:229], v180 offset:0x3200
	ds_read_b64_tr_b16 v[230:231], v180 offset:0x3a00
	v_mov_b32_e32 v239, v238
	s_nop 1
	v_permlane32_swap_b32_e32 v238, v239
	v_max_f32_e32 v239, v239, v239
	v_max_f32_e32 v238, v238, v238
	v_max_f32_e32 v238, v238, v239
	s_waitcnt lgkmcnt(6)
; #define SBAR() __builtin_amdgcn_sched_barrier(0)
; template <int OFF> __device__ __forceinline__ s16x4 tr_read(int vb) { s16x4 r; asm volatile("ds_read_b64_tr_b16 %0, %1 offset:%2" : "=&v"(r) : "v"(vb), "i"(OFF) : "memory"); return r; }
; template <int D0> __device__ __forceinline__ void pv_one(f32x16& od, int vb, bf16x8 pa0, bf16x8 pa1, bf16x8 pa2, bf16x8 pa3) {
;     const s16x4 l0 = tr_read<v_rd_off(D0, 0, 0)>(vb), h0 = tr_read<v_rd_off(D0, 0, 1)>(vb), l1 = tr_read<v_rd_off(D0, 1, 0)>(vb), h1 = tr_read<v_rd_off(D0, 1, 1)>(vb);
;     const s16x4 l2 = tr_read<v_rd_off(D0, 2, 0)>(vb), h2 = tr_read<v_rd_off(D0, 2, 1)>(vb), l3 = tr_read<v_rd_off(D0, 3, 0)>(vb), h3 = tr_read<v_rd_off(D0, 3, 1)>(vb);
;     asm volatile("s_waitcnt lgkmcnt(0)" ::: "memory"); SBAR();
;     ...
;     od = __builtin_amdgcn_mfma_f32_32x32x16_bf16(pa0, PK(l0, h0), od, 0, 0, 0);
;     od = __builtin_amdgcn_mfma_f32_32x32x16_bf16(pa1, PK(l1, h1), od, 0, 0, 0);
;     od = __builtin_amdgcn_mfma_f32_32x32x16_bf16(pa2, PK(l2, h2), od, 0, 0, 0);
;     od = __builtin_amdgcn_mfma_f32_32x32x16_bf16(pa3, PK(l3, h3), od, 0, 0, 0);
;     ...
; }
; __device__ __forceinline__ void pv_d0(f32x16* o, int vb, bf16x8 pa0, bf16x8 pa1, bf16x8 pa2, bf16x8 pa3) {
;     pv_one<0>(o[0], vb, pa0, pa1, pa2, pa3); pv_one<1>(o[1], vb, pa0, pa1, pa2, pa3); pv_one<2>(o[2], vb, pa0, pa1, pa2, pa3); pv_one<3>(o[3], vb, pa0, pa1, pa2, pa3);
; }
; __device__ __forceinline__ void partialSM(f32x16& p0, f32x16& p1, float& m_reg, float& mn, float& alpha, const float C, const float thr) {
;     float pmax = p0[0];
; #pragma unroll
;     for (int r = 1; r < 16; ++r) pmax = fmaxf(pmax, p0[r]);
; #pragma unroll
;     for (int r = 0; r < 16; ++r) pmax = fmaxf(pmax, p1[r]);
;     { auto rr = __builtin_amdgcn_permlane32_swap(__float_as_uint(pmax), __float_as_uint(pmax), false, false);
;       pmax = fmaxf(__uint_as_float(rr[0]), __uint_as_float(rr[1])); }
;     if (__builtin_expect(__all(pmax - m_reg <= thr), 1)) { mn = m_reg; alpha = 1.f; }
;     else { mn = fmaxf(m_reg, pmax); alpha = __builtin_amdgcn_exp2f((m_reg - mn) * C); m_reg = mn; }
;     const float mnC = -mn * C;
; #pragma unroll
;     for (int r = 0; r < 16; ++r) p0[r] = fmaf(p0[r], C, mnC);
; #pragma unroll
;     for (int r = 0; r < 16; ++r) p1[r] = fmaf(p1[r], C, mnC);
; #pragma unroll
;     for (int r = 0; r < 16; ++r) p0[r] = __builtin_amdgcn_exp2f(p0[r]);
; }
	v_mfma_f32_32x32x16_bf16 v[32:47], v[138:141], v[216:219], v[32:47]
	ds_read_b64_tr_b16 v[216:217], v180 offset:0x400
	ds_read_b64_tr_b16 v[218:219], v180 offset:0xc00
	v_sub_f32_e32 v239, v238, v142
	v_cmp_ge_f32_e32 vcc, s76, v239
	v_max_f32_e32 v239, v142, v142
	v_max_f32_e32 v238, v239, v238
	v_sub_f32_e32 v239, v142, v238
	v_mul_f32_e32 v239, 0x3e38aa3b, v239
	s_waitcnt lgkmcnt(6)
	v_mfma_f32_32x32x16_bf16 v[32:47], v[204:207], v[220:223], v[32:47]
	ds_read_b64_tr_b16 v[220:221], v180 offset:0x1400
	ds_read_b64_tr_b16 v[222:223], v180 offset:0x1c00
	v_exp_f32_e32 v239, v239
	s_cmp_eq_u64 vcc, exec
	s_cselect_b64 s[14:15], -1, 0
	v_cndmask_b32_e64 v200, v239, 1.0, s[14:15]
	v_cmp_gt_f32_e32 vcc, 1.0, v200
	s_waitcnt lgkmcnt(6)
	v_mfma_f32_32x32x16_bf16 v[32:47], v[144:147], v[224:227], v[32:47]
	ds_read_b64_tr_b16 v[224:225], v180 offset:0x2400
	ds_read_b64_tr_b16 v[226:227], v180 offset:0x2c00
	v_cndmask_b32_e64 v241, v238, v142, s[14:15]
	v_mul_f32_e32 v239, 0xbe38aa3b, v241
	v_fmamk_f32 v80, v80, 0x3e38aa3b, v239
	v_fmamk_f32 v81, v81, 0x3e38aa3b, v239
	s_waitcnt lgkmcnt(6)
	v_mfma_f32_32x32x16_bf16 v[32:47], v[148:151], v[228:231], v[32:47]
	ds_read_b64_tr_b16 v[228:229], v180 offset:0x3400
	ds_read_b64_tr_b16 v[230:231], v180 offset:0x3c00
	v_fmamk_f32 v82, v82, 0x3e38aa3b, v239
	v_fmamk_f32 v83, v83, 0x3e38aa3b, v239
	v_fmamk_f32 v84, v84, 0x3e38aa3b, v239
	v_fmamk_f32 v85, v85, 0x3e38aa3b, v239
	s_waitcnt lgkmcnt(6)
	v_mfma_f32_32x32x16_bf16 v[16:31], v[138:141], v[216:219], v[16:31]
	ds_read_b64_tr_b16 v[216:217], v180 offset:0x600
	ds_read_b64_tr_b16 v[218:219], v180 offset:0xe00
	v_fmamk_f32 v86, v86, 0x3e38aa3b, v239
	v_fmamk_f32 v87, v87, 0x3e38aa3b, v239
	v_fmamk_f32 v88, v88, 0x3e38aa3b, v239
	v_fmamk_f32 v89, v89, 0x3e38aa3b, v239
	s_waitcnt lgkmcnt(6)
	v_mfma_f32_32x32x16_bf16 v[16:31], v[204:207], v[220:223], v[16:31]
	ds_read_b64_tr_b16 v[220:221], v180 offset:0x1600
	ds_read_b64_tr_b16 v[222:223], v180 offset:0x1e00
	v_fmamk_f32 v90, v90, 0x3e38aa3b, v239
	v_fmamk_f32 v91, v91, 0x3e38aa3b, v239
	v_fmamk_f32 v92, v92, 0x3e38aa3b, v239
	v_fmamk_f32 v93, v93, 0x3e38aa3b, v239
	s_waitcnt lgkmcnt(6)
	v_mfma_f32_32x32x16_bf16 v[16:31], v[144:147], v[224:227], v[16:31]
	ds_read_b64_tr_b16 v[224:225], v180 offset:0x2600
	ds_read_b64_tr_b16 v[226:227], v180 offset:0x2e00
	v_fmamk_f32 v94, v94, 0x3e38aa3b, v239
	v_fmamk_f32 v95, v95, 0x3e38aa3b, v239
	s_waitcnt lgkmcnt(6)
	v_mfma_f32_32x32x16_bf16 v[16:31], v[148:151], v[228:231], v[16:31]
	ds_read_b64_tr_b16 v[228:229], v180 offset:0x3600
	ds_read_b64_tr_b16 v[230:231], v180 offset:0x3e00
	v_exp_f32_e32 v153, v81
	v_exp_f32_e32 v152, v83
	v_exp_f32_e32 v142, v88
	v_exp_f32_e32 v143, v90
	s_waitcnt lgkmcnt(6)
	v_mfma_f32_32x32x16_bf16 v[0:15], v[138:141], v[216:219], v[0:15]
	s_waitcnt lgkmcnt(4)
	v_mfma_f32_32x32x16_bf16 v[0:15], v[204:207], v[220:223], v[0:15]
	v_exp_f32_e32 v138, v80
	s_waitcnt lgkmcnt(2)
	v_mfma_f32_32x32x16_bf16 v[0:15], v[144:147], v[224:227], v[0:15]
	v_exp_f32_e32 v144, v92
	v_exp_f32_e32 v147, v93
	v_exp_f32_e32 v145, v94
	v_exp_f32_e32 v146, v95
	v_exp_f32_e32 v139, v82
	s_waitcnt lgkmcnt(0)
	v_mfma_f32_32x32x16_bf16 v[0:15], v[148:151], v[228:231], v[0:15]
	v_exp_f32_e32 v140, v84
	v_exp_f32_e32 v141, v86
	s_barrier
	s_waitcnt vmcnt(5)
	ds_write_b128 v181, v[114:117]
	s_waitcnt vmcnt(4)
	ds_write_b128 v184, v[118:121]
	s_waitcnt vmcnt(3)
	ds_write_b128 v182, v[122:125] offset:32768
	s_cbranch_vccz .LBB0_175
	s_and_saveexec_b64 s[38:39], s[12:13]
	ds_write_b32 v177, v200 offset:49280
	s_or_b64 exec, exec, s[38:39]
	s_waitcnt lgkmcnt(0)
	v_add_u32_e32 v242, v161, v96
	ds_read_b128 v[244:247], v242 offset:49376
	ds_read_b128 v[148:151], v242 offset:49344
	ds_read_b128 v[204:207], v242 offset:49312
	ds_read_b128 v[216:219], v242 offset:49280
	s_waitcnt lgkmcnt(3)
	v_pk_mul_f32 v[60:61], v[60:61], v[244:245]
	s_waitcnt lgkmcnt(2)
	v_pk_mul_f32 v[56:57], v[56:57], v[148:149]
	s_waitcnt lgkmcnt(1)
	v_pk_mul_f32 v[52:53], v[52:53], v[204:205]
	v_pk_mul_f32 v[62:63], v[62:63], v[246:247]
	v_pk_mul_f32 v[58:59], v[58:59], v[150:151]
	v_pk_mul_f32 v[54:55], v[54:55], v[206:207]
	s_waitcnt lgkmcnt(0)
	v_pk_mul_f32 v[50:51], v[50:51], v[218:219]
	v_pk_mul_f32 v[48:49], v[48:49], v[216:217]
	v_pk_mul_f32 v[44:45], v[44:45], v[244:245]
	v_pk_mul_f32 v[40:41], v[40:41], v[148:149]
	v_pk_mul_f32 v[36:37], v[36:37], v[204:205]
	v_pk_mul_f32 v[46:47], v[46:47], v[246:247]
	v_pk_mul_f32 v[42:43], v[42:43], v[150:151]
	v_pk_mul_f32 v[38:39], v[38:39], v[206:207]
	v_pk_mul_f32 v[34:35], v[34:35], v[218:219]
	v_pk_mul_f32 v[32:33], v[32:33], v[216:217]
	v_pk_mul_f32 v[28:29], v[28:29], v[244:245]
	v_pk_mul_f32 v[24:25], v[24:25], v[148:149]
	v_pk_mul_f32 v[20:21], v[20:21], v[204:205]
	v_pk_mul_f32 v[30:31], v[30:31], v[246:247]
	v_pk_mul_f32 v[26:27], v[26:27], v[150:151]
	v_pk_mul_f32 v[22:23], v[22:23], v[206:207]
	v_pk_mul_f32 v[18:19], v[18:19], v[218:219]
	v_pk_mul_f32 v[16:17], v[16:17], v[216:217]
	v_pk_mul_f32 v[12:13], v[12:13], v[244:245]
	v_pk_mul_f32 v[8:9], v[8:9], v[148:149]
	v_pk_mul_f32 v[4:5], v[4:5], v[204:205]
	v_pk_mul_f32 v[14:15], v[14:15], v[246:247]
	v_pk_mul_f32 v[10:11], v[10:11], v[150:151]
	v_pk_mul_f32 v[6:7], v[6:7], v[206:207]
	v_pk_mul_f32 v[2:3], v[2:3], v[218:219]
	v_pk_mul_f32 v[0:1], v[0:1], v[216:217]

; #define SBAR() __builtin_amdgcn_sched_barrier(0)
; template <int OFF> __device__ __forceinline__ s16x4 tr_read(int vb) { s16x4 r; asm volatile("ds_read_b64_tr_b16 %0, %1 offset:%2" : "=&v"(r) : "v"(vb), "i"(OFF) : "memory"); return r; }
; template <int D0> __device__ __forceinline__ void pv_one(f32x16& od, int vb, bf16x8 pa0, bf16x8 pa1, bf16x8 pa2, bf16x8 pa3) {
;     const s16x4 l0 = tr_read<v_rd_off(D0, 0, 0)>(vb), h0 = tr_read<v_rd_off(D0, 0, 1)>(vb), l1 = tr_read<v_rd_off(D0, 1, 0)>(vb), h1 = tr_read<v_rd_off(D0, 1, 1)>(vb);
;     const s16x4 l2 = tr_read<v_rd_off(D0, 2, 0)>(vb), h2 = tr_read<v_rd_off(D0, 2, 1)>(vb), l3 = tr_read<v_rd_off(D0, 3, 0)>(vb), h3 = tr_read<v_rd_off(D0, 3, 1)>(vb);
;     asm volatile("s_waitcnt lgkmcnt(0)" ::: "memory"); SBAR();
;     ...
;     od = __builtin_amdgcn_mfma_f32_32x32x16_bf16(pa0, PK(l0, h0), od, 0, 0, 0);
;     od = __builtin_amdgcn_mfma_f32_32x32x16_bf16(pa1, PK(l1, h1), od, 0, 0, 0);
;     od = __builtin_amdgcn_mfma_f32_32x32x16_bf16(pa2, PK(l2, h2), od, 0, 0, 0);
;     od = __builtin_amdgcn_mfma_f32_32x32x16_bf16(pa3, PK(l3, h3), od, 0, 0, 0);
;     ...
; }
; __device__ __forceinline__ void pv_d0(f32x16* o, int vb, bf16x8 pa0, bf16x8 pa1, bf16x8 pa2, bf16x8 pa3) {
;     pv_one<0>(o[0], vb, pa0, pa1, pa2, pa3); pv_one<1>(o[1], vb, pa0, pa1, pa2, pa3); pv_one<2>(o[2], vb, pa0, pa1, pa2, pa3); pv_one<3>(o[3], vb, pa0, pa1, pa2, pa3);
; }
; __device__ __forceinline__ void partialSM(f32x16& p0, f32x16& p1, float& m_reg, float& mn, float& alpha, const float C, const float thr) {
;     float pmax = p0[0];
; #pragma unroll
;     for (int r = 1; r < 16; ++r) pmax = fmaxf(pmax, p0[r]);
; #pragma unroll
;     for (int r = 0; r < 16; ++r) pmax = fmaxf(pmax, p1[r]);
;     { auto rr = __builtin_amdgcn_permlane32_swap(__float_as_uint(pmax), __float_as_uint(pmax), false, false);
;       pmax = fmaxf(__uint_as_float(rr[0]), __uint_as_float(rr[1])); }
;     if (__builtin_expect(__all(pmax - m_reg <= thr), 1)) { mn = m_reg; alpha = 1.f; }
;     else { mn = fmaxf(m_reg, pmax); alpha = __builtin_amdgcn_exp2f((m_reg - mn) * C); m_reg = mn; }
;     const float mnC = -mn * C;
; #pragma unroll
;     for (int r = 0; r < 16; ++r) p0[r] = fmaf(p0[r], C, mnC);
; #pragma unroll
;     for (int r = 0; r < 16; ++r) p1[r] = fmaf(p1[r], C, mnC);
; #pragma unroll
;     for (int r = 0; r < 16; ++r) p0[r] = __builtin_amdgcn_exp2f(p0[r]);
; }
.LBB0_177:
	s_waitcnt lgkmcnt(0)
	s_nop 0
	v_mfma_f32_32x32x16_bf16 v[48:63], v[138:141], v[216:219], v[48:63]
	ds_read_b64_tr_b16 v[216:217], v179 offset:0x200
	ds_read_b64_tr_b16 v[218:219], v179 offset:0xa00
	v_max_f32_e32 v238, v81, v81
	v_max_f32_e32 v239, v80, v80
	v_max_f32_e32 v238, v239, v238
	v_max3_f32 v238, v238, v82, v83
	v_max3_f32 v238, v238, v84, v85
	v_max3_f32 v238, v238, v86, v87
	v_mfma_f32_32x32x16_bf16 v[48:63], v[142:145], v[220:223], v[48:63]
	ds_read_b64_tr_b16 v[220:221], v179 offset:0x1200
	ds_read_b64_tr_b16 v[222:223], v179 offset:0x1a00
	v_max3_f32 v238, v238, v88, v89
	v_max3_f32 v238, v238, v90, v91
	v_max3_f32 v238, v238, v92, v93
	v_max3_f32 v238, v238, v94, v95
	v_max3_f32 v238, v238, v64, v65
	v_max3_f32 v238, v238, v66, v67
	v_mfma_f32_32x32x16_bf16 v[48:63], v[146:149], v[224:227], v[48:63]
	ds_read_b64_tr_b16 v[224:225], v179 offset:0x2200
	ds_read_b64_tr_b16 v[226:227], v179 offset:0x2a00
	v_max3_f32 v238, v238, v68, v69
	v_max3_f32 v238, v238, v70, v71
	v_max3_f32 v238, v238, v72, v73
	v_max3_f32 v238, v238, v74, v75
	v_max3_f32 v238, v238, v76, v77
	v_max3_f32 v238, v238, v78, v79
	v_mfma_f32_32x32x16_bf16 v[48:63], v[150:153], v[228:231], v[48:63]
	ds_read_b64_tr_b16 v[228:229], v179 offset:0x3200
	ds_read_b64_tr_b16 v[230:231], v179 offset:0x3a00
	v_mov_b32_e32 v239, v238
	s_nop 1
	v_permlane32_swap_b32_e32 v238, v239
	v_max_f32_e32 v239, v239, v239
	v_max_f32_e32 v238, v238, v238
	v_max_f32_e32 v238, v238, v239
	s_waitcnt lgkmcnt(6)
	v_mfma_f32_32x32x16_bf16 v[32:47], v[138:141], v[216:219], v[32:47]
	ds_read_b64_tr_b16 v[216:217], v179 offset:0x400
	ds_read_b64_tr_b16 v[218:219], v179 offset:0xc00
	v_sub_f32_e32 v239, v238, v202
	v_cmp_ge_f32_e32 vcc, s76, v239
	v_max_f32_e32 v239, v202, v202
	v_max_f32_e32 v238, v239, v238
	v_sub_f32_e32 v239, v202, v238
	v_mul_f32_e32 v239, 0x3e38aa3b, v239
	s_waitcnt lgkmcnt(6)
	v_mfma_f32_32x32x16_bf16 v[32:47], v[142:145], v[220:223], v[32:47]
	ds_read_b64_tr_b16 v[220:221], v179 offset:0x1400
	ds_read_b64_tr_b16 v[222:223], v179 offset:0x1c00
	v_exp_f32_e32 v239, v239
	s_cmp_eq_u64 vcc, exec
	s_cselect_b64 s[14:15], -1, 0
	v_cndmask_b32_e64 v240, v239, 1.0, s[14:15]
	v_cmp_gt_f32_e32 vcc, 1.0, v240
	s_waitcnt lgkmcnt(6)
	v_mfma_f32_32x32x16_bf16 v[32:47], v[146:149], v[224:227], v[32:47]
	ds_read_b64_tr_b16 v[224:225], v179 offset:0x2400
	ds_read_b64_tr_b16 v[226:227], v179 offset:0x2c00
	v_cndmask_b32_e64 v241, v238, v202, s[14:15]
	v_mul_f32_e32 v239, 0xbe38aa3b, v241
	v_fmamk_f32 v80, v80, 0x3e38aa3b, v239
	v_fmamk_f32 v81, v81, 0x3e38aa3b, v239
	s_waitcnt lgkmcnt(6)
	v_mfma_f32_32x32x16_bf16 v[32:47], v[150:153], v[228:231], v[32:47]
	ds_read_b64_tr_b16 v[228:229], v179 offset:0x3400
	ds_read_b64_tr_b16 v[230:231], v179 offset:0x3c00
	v_fmamk_f32 v82, v82, 0x3e38aa3b, v239
	v_fmamk_f32 v83, v83, 0x3e38aa3b, v239
	v_fmamk_f32 v84, v84, 0x3e38aa3b, v239
	v_fmamk_f32 v85, v85, 0x3e38aa3b, v239
	s_waitcnt lgkmcnt(6)
	v_mfma_f32_32x32x16_bf16 v[16:31], v[138:141], v[216:219], v[16:31]
	ds_read_b64_tr_b16 v[216:217], v179 offset:0x600
	ds_read_b64_tr_b16 v[218:219], v179 offset:0xe00
	v_fmamk_f32 v86, v86, 0x3e38aa3b, v239
	v_fmamk_f32 v87, v87, 0x3e38aa3b, v239
	v_fmamk_f32 v88, v88, 0x3e38aa3b, v239
	v_fmamk_f32 v89, v89, 0x3e38aa3b, v239
	s_waitcnt lgkmcnt(6)
	v_mfma_f32_32x32x16_bf16 v[16:31], v[142:145], v[220:223], v[16:31]
	ds_read_b64_tr_b16 v[220:221], v179 offset:0x1600
	ds_read_b64_tr_b16 v[222:223], v179 offset:0x1e00
	v_fmamk_f32 v90, v90, 0x3e38aa3b, v239
	v_fmamk_f32 v91, v91, 0x3e38aa3b, v239
	v_fmamk_f32 v92, v92, 0x3e38aa3b, v239
	v_fmamk_f32 v93, v93, 0x3e38aa3b, v239
	s_waitcnt lgkmcnt(6)
	v_mfma_f32_32x32x16_bf16 v[16:31], v[146:149], v[224:227], v[16:31]
	ds_read_b64_tr_b16 v[224:225], v179 offset:0x2600
	ds_read_b64_tr_b16 v[226:227], v179 offset:0x2e00
	v_fmamk_f32 v94, v94, 0x3e38aa3b, v239
	s_waitcnt lgkmcnt(6)
	v_mfma_f32_32x32x16_bf16 v[16:31], v[150:153], v[228:231], v[16:31]
	ds_read_b64_tr_b16 v[228:229], v179 offset:0x3600
	ds_read_b64_tr_b16 v[230:231], v179 offset:0x3e00
	v_exp_f32_e32 v208, v82
	v_exp_f32_e32 v202, v87
	s_waitcnt lgkmcnt(6)
	v_mfma_f32_32x32x16_bf16 v[0:15], v[138:141], v[216:219], v[0:15]
	s_waitcnt lgkmcnt(4)
	v_mfma_f32_32x32x16_bf16 v[0:15], v[142:145], v[220:223], v[0:15]
	v_exp_f32_e32 v145, v92
	v_exp_f32_e32 v144, v94
	v_exp_f32_e32 v217, v80
	s_waitcnt lgkmcnt(2)
	v_mfma_f32_32x32x16_bf16 v[0:15], v[146:149], v[224:227], v[0:15]
	v_exp_f32_e32 v149, v88
	v_exp_f32_e32 v147, v90
	v_exp_f32_e32 v148, v93
	v_exp_f32_e32 v219, v81
	s_waitcnt lgkmcnt(0)
	v_mfma_f32_32x32x16_bf16 v[0:15], v[150:153], v[228:231], v[0:15]
	v_exp_f32_e32 v218, v83
	v_exp_f32_e32 v216, v85
	v_mov_b32_e32 v143, v240
	s_barrier
	s_waitcnt vmcnt(2)
	ds_write_b128 v181, v[126:129] offset:16384
	s_waitcnt vmcnt(1)
	ds_write_b128 v184, v[130:133] offset:16384
	s_waitcnt vmcnt(0)
	ds_write_b128 v182, v[134:137] offset:40960
	s_cbranch_vccz .LBB0_181
	s_and_saveexec_b64 s[38:39], s[12:13]
	ds_write_b32 v177, v143 offset:49280
	s_or_b64 exec, exec, s[38:39]
	s_waitcnt lgkmcnt(0)
	v_add_u32_e32 v139, v161, v96
	ds_read_b128 v[126:129], v139 offset:49376
	ds_read_b128 v[130:133], v139 offset:49344
	ds_read_b128 v[134:137], v139 offset:49312
	ds_read_b128 v[244:247], v139 offset:49280
	s_waitcnt lgkmcnt(3)
	v_pk_mul_f32 v[60:61], v[60:61], v[126:127]
	s_waitcnt lgkmcnt(2)
	v_pk_mul_f32 v[56:57], v[56:57], v[130:131]
	s_waitcnt lgkmcnt(1)
	v_pk_mul_f32 v[52:53], v[52:53], v[134:135]
	v_pk_mul_f32 v[62:63], v[62:63], v[128:129]
	v_pk_mul_f32 v[58:59], v[58:59], v[132:133]
	v_pk_mul_f32 v[54:55], v[54:55], v[136:137]
	s_waitcnt lgkmcnt(0)
	v_pk_mul_f32 v[50:51], v[50:51], v[246:247]
	v_pk_mul_f32 v[48:49], v[48:49], v[244:245]
	v_pk_mul_f32 v[44:45], v[44:45], v[126:127]
	v_pk_mul_f32 v[40:41], v[40:41], v[130:131]
	v_pk_mul_f32 v[36:37], v[36:37], v[134:135]
	v_pk_mul_f32 v[46:47], v[46:47], v[128:129]
	v_pk_mul_f32 v[42:43], v[42:43], v[132:133]
	v_pk_mul_f32 v[38:39], v[38:39], v[136:137]
	v_pk_mul_f32 v[34:35], v[34:35], v[246:247]
	v_pk_mul_f32 v[32:33], v[32:33], v[244:245]
	v_pk_mul_f32 v[28:29], v[28:29], v[126:127]
	v_pk_mul_f32 v[24:25], v[24:25], v[130:131]
	v_pk_mul_f32 v[20:21], v[20:21], v[134:135]
	v_pk_mul_f32 v[30:31], v[30:31], v[128:129]
	v_pk_mul_f32 v[26:27], v[26:27], v[132:133]
	v_pk_mul_f32 v[22:23], v[22:23], v[136:137]
	v_pk_mul_f32 v[18:19], v[18:19], v[246:247]
	v_pk_mul_f32 v[16:17], v[16:17], v[244:245]
	v_pk_mul_f32 v[12:13], v[12:13], v[126:127]
	v_pk_mul_f32 v[8:9], v[8:9], v[130:131]
	v_pk_mul_f32 v[4:5], v[4:5], v[134:135]
	v_pk_mul_f32 v[14:15], v[14:15], v[128:129]
	v_pk_mul_f32 v[10:11], v[10:11], v[132:133]
	v_pk_mul_f32 v[6:7], v[6:7], v[136:137]
	v_pk_mul_f32 v[2:3], v[2:3], v[246:247]
	v_pk_mul_f32 v[0:1], v[0:1], v[244:245]

; #define SBAR() __builtin_amdgcn_sched_barrier(0)
; template <int DQK, int DK1, int LDQ, int LDK, int LDKR, int LDV, int NQL, int SDEPTH>
; __device__ __forceinline__ void attn_core(const AttnArgs& a, char* lds, f32x16 (&o)[4]) {
;     ...
;         SBAR(); QKT(pB0, pB1, K_lds + SHM_K);
;         finishSM(pA0, pA1, alA, l_reg, pa0, pa1, pa2, pa3); SBAR();
.LBB0_219:
	ds_read_b128 v[64:67], v184 offset:57344
	ds_read_b128 v[68:71], v216 offset:12288
	ds_read_b128 v[222:225], v192 offset:57344
	ds_read_b128 v[226:229], v208 offset:12288
	v_exp_f32_e32 v207, v130
	v_add_f32_e32 v130, 0, v219
	s_waitcnt lgkmcnt(3)
	v_mfma_f32_32x32x16_bf16 v[80:95], v[64:67], v[126:129], 0
	v_add_f32_e32 v130, v221, v130
	v_add_f32_e32 v130, v157, v130
	v_add_f32_e32 v130, v220, v130
	v_add_f32_e32 v130, v156, v130
	v_add_f32_e32 v130, v218, v130
	v_add_f32_e32 v130, v154, v130
	v_add_f32_e32 v130, v155, v130
	s_waitcnt lgkmcnt(2)
	v_mfma_f32_32x32x16_bf16 v[64:79], v[68:71], v[126:129], 0
	v_add_f32_e32 v130, v151, v130
	v_add_f32_e32 v130, v153, v130
	v_add_f32_e32 v130, v150, v130
	v_add_f32_e32 v130, v152, v130
	v_exp_f32_e32 v142, v142
	v_add_f32_e32 v130, v147, v130
	v_exp_f32_e32 v143, v143
	s_waitcnt lgkmcnt(1)
	v_mfma_f32_32x32x16_bf16 v[80:95], v[222:225], v[122:125], v[80:95]
	v_add_f32_e32 v130, v149, v130
	v_exp_f32_e32 v140, v140
	v_add_f32_e32 v130, v146, v130
	v_exp_f32_e32 v141, v141
	v_add_f32_e32 v130, v148, v130
	v_exp_f32_e32 v134, v134
	v_add_f32_e32 v130, v142, v130
	s_waitcnt lgkmcnt(0)
	v_mfma_f32_32x32x16_bf16 v[64:79], v[226:229], v[122:125], v[64:79]
	ds_read_b128 v[222:225], v190 offset:57344
	ds_read_b128 v[226:229], v206 offset:12288
	v_exp_f32_e32 v135, v135
	v_add_f32_e32 v130, v143, v130
	v_exp_f32_e32 v191, v132
	v_add_f32_e32 v130, v140, v130
	v_exp_f32_e32 v205, v133
	v_add_f32_e32 v130, v141, v130
	s_waitcnt lgkmcnt(1)
	v_mfma_f32_32x32x16_bf16 v[80:95], v[222:225], v[118:121], v[80:95]
	v_add_f32_e32 v130, v134, v130
	v_exp_f32_e32 v210, v131
	v_add_f32_e32 v130, v135, v130
	v_exp_f32_e32 v144, v144
	v_add_f32_e32 v130, v191, v130
	v_exp_f32_e32 v145, v145
	v_add_f32_e32 v130, v205, v130
	s_waitcnt lgkmcnt(0)
	v_mfma_f32_32x32x16_bf16 v[64:79], v[226:229], v[118:121], v[64:79]
	ds_read_b128 v[222:225], v173 offset:57344
	ds_read_b128 v[226:229], v202 offset:12288
	v_exp_f32_e32 v138, v138
	v_add_f32_e32 v130, v207, v130
	v_exp_f32_e32 v139, v139
	v_add_f32_e32 v130, v210, v130
	v_exp_f32_e32 v136, v136
	v_add_f32_e32 v130, v144, v130
	s_waitcnt lgkmcnt(1)
	v_mfma_f32_32x32x16_bf16 v[80:95], v[222:225], v[114:117], v[80:95]
	v_exp_f32_e32 v137, v137
	v_add_f32_e32 v130, v145, v130
	v_add_f32_e32 v130, v138, v130
	v_add_f32_e32 v130, v139, v130
	v_add_f32_e32 v130, v136, v130
	s_waitcnt lgkmcnt(0)
	v_mfma_f32_32x32x16_bf16 v[64:79], v[226:229], v[114:117], v[64:79]
	ds_read_b128 v[222:225], v184 offset:57472
	ds_read_b128 v[226:229], v216 offset:12416
	s_waitcnt lgkmcnt(1)
	v_mfma_f32_32x32x16_bf16 v[80:95], v[222:225], v[110:113], v[80:95]
	s_waitcnt lgkmcnt(0)
	v_mfma_f32_32x32x16_bf16 v[64:79], v[226:229], v[110:113], v[64:79]
	ds_read_b128 v[222:225], v192 offset:57472
	ds_read_b128 v[226:229], v208 offset:12416
	s_waitcnt lgkmcnt(1)
	v_mfma_f32_32x32x16_bf16 v[80:95], v[222:225], v[106:109], v[80:95]
	s_waitcnt lgkmcnt(0)
	v_mfma_f32_32x32x16_bf16 v[64:79], v[226:229], v[106:109], v[64:79]
	ds_read_b128 v[222:225], v190 offset:57472
	ds_read_b128 v[226:229], v206 offset:12416
	s_waitcnt lgkmcnt(1)
	v_mfma_f32_32x32x16_bf16 v[80:95], v[222:225], v[102:105], v[80:95]
	s_waitcnt lgkmcnt(0)
	v_mfma_f32_32x32x16_bf16 v[64:79], v[226:229], v[102:105], v[64:79]
	ds_read_b128 v[222:225], v173 offset:57472
	ds_read_b128 v[226:229], v202 offset:12416
	s_waitcnt lgkmcnt(1)
	v_mfma_f32_32x32x16_bf16 v[80:95], v[222:225], v[98:101], v[80:95]
	s_waitcnt lgkmcnt(0)
	v_mfma_f32_32x32x16_bf16 v[64:79], v[226:229], v[98:101], v[64:79]
	ds_read_b128 v[222:225], v184 offset:57600
	ds_read_b128 v[226:229], v216 offset:12544
	ds_read_b128 v[230:233], v181
	s_waitcnt lgkmcnt(0)
	v_mfma_f32_32x32x16_bf16 v[80:95], v[222:225], v[230:233], v[80:95]
	v_mfma_f32_32x32x16_bf16 v[64:79], v[226:229], v[230:233], v[64:79]
	ds_read_b128 v[222:225], v192 offset:57600
	ds_read_b128 v[226:229], v208 offset:12544
	ds_read_b128 v[230:233], v181 offset:8192
	s_waitcnt lgkmcnt(0)
	v_mfma_f32_32x32x16_bf16 v[80:95], v[222:225], v[230:233], v[80:95]
	v_mfma_f32_32x32x16_bf16 v[64:79], v[226:229], v[230:233], v[64:79]
	ds_read_b128 v[222:225], v190 offset:57600
	ds_read_b128 v[226:229], v206 offset:12544
	ds_read_b128 v[230:233], v181 offset:16384
	s_waitcnt lgkmcnt(0)
	v_mfma_f32_32x32x16_bf16 v[80:95], v[222:225], v[230:233], v[80:95]
	v_mfma_f32_32x32x16_bf16 v[64:79], v[226:229], v[230:233], v[64:79]
	ds_read_b128 v[222:225], v173 offset:57600
	ds_read_b128 v[226:229], v202 offset:12544
	ds_read_b128 v[230:233], v181 offset:24576
	s_waitcnt lgkmcnt(0)
; template <int D0> __device__ __forceinline__ void pv_one(f32x16& od, int vb, bf16x8 pa0, bf16x8 pa1, bf16x8 pa2, bf16x8 pa3) {
;     const s16x4 l0 = tr_read<v_rd_off(D0, 0, 0)>(vb), h0 = tr_read<v_rd_off(D0, 0, 1)>(vb), l1 = tr_read<v_rd_off(D0, 1, 0)>(vb), h1 = tr_read<v_rd_off(D0, 1, 1)>(vb);
;     const s16x4 l2 = tr_read<v_rd_off(D0, 2, 0)>(vb), h2 = tr_read<v_rd_off(D0, 2, 1)>(vb), l3 = tr_read<v_rd_off(D0, 3, 0)>(vb), h3 = tr_read<v_rd_off(D0, 3, 1)>(vb);
;     asm volatile("s_waitcnt lgkmcnt(0)" ::: "memory"); SBAR();
;     ...
;     od = __builtin_amdgcn_mfma_f32_32x32x16_bf16(pa0, PK(l0, h0), od, 0, 0, 0);
;     od = __builtin_amdgcn_mfma_f32_32x32x16_bf16(pa1, PK(l1, h1), od, 0, 0, 0);
;     od = __builtin_amdgcn_mfma_f32_32x32x16_bf16(pa2, PK(l2, h2), od, 0, 0, 0);
;     od = __builtin_amdgcn_mfma_f32_32x32x16_bf16(pa3, PK(l3, h3), od, 0, 0, 0);
;     ...
; }
; __device__ __forceinline__ void pv_d0(f32x16* o, int vb, bf16x8 pa0, bf16x8 pa1, bf16x8 pa2, bf16x8 pa3) {
;     pv_one<0>(o[0], vb, pa0, pa1, pa2, pa3); pv_one<1>(o[1], vb, pa0, pa1, pa2, pa3); pv_one<2>(o[2], vb, pa0, pa1, pa2, pa3); pv_one<3>(o[3], vb, pa0, pa1, pa2, pa3);
; }
; __device__ __forceinline__ void partialSM(f32x16& p0, f32x16& p1, float& m_reg, float& mn, float& alpha, const float C, const float thr) {
;     float pmax = p0[0];
; #pragma unroll
;     for (int r = 1; r < 16; ++r) pmax = fmaxf(pmax, p0[r]);
; #pragma unroll
;     for (int r = 0; r < 16; ++r) pmax = fmaxf(pmax, p1[r]);
;     { auto rr = __builtin_amdgcn_permlane32_swap(__float_as_uint(pmax), __float_as_uint(pmax), false, false);
;       pmax = fmaxf(__uint_as_float(rr[0]), __uint_as_float(rr[1])); }
;     if (__builtin_expect(__all(pmax - m_reg <= thr), 1)) { mn = m_reg; alpha = 1.f; }
;     else { mn = fmaxf(m_reg, pmax); alpha = __builtin_amdgcn_exp2f((m_reg - mn) * C); m_reg = mn; }
;     const float mnC = -mn * C;
; #pragma unroll
;     for (int r = 0; r < 16; ++r) p0[r] = fmaf(p0[r], C, mnC);
; #pragma unroll
;     for (int r = 0; r < 16; ++r) p1[r] = fmaf(p1[r], C, mnC);
; #pragma unroll
;     for (int r = 0; r < 16; ++r) p0[r] = __builtin_amdgcn_exp2f(p0[r]);
; }
; __device__ __forceinline__ void finishSM(f32x16& p0, f32x16& p1, float alpha, float& l_reg, bf16x8& pa0, bf16x8& pa1, bf16x8& pa2, bf16x8& pa3) {
; #pragma unroll
;     for (int r = 0; r < 16; ++r) p1[r] = __builtin_amdgcn_exp2f(p1[r]);
;     float ps = 0;
	v_mfma_f32_32x32x16_bf16 v[80:95], v[222:225], v[230:233], v[80:95]
	v_add_f32_e32 v222, v137, v130
	v_mov_b32_e32 v223, v222
	v_cvt_pk_bf16_f32 v130, v219, v221
	v_cvt_pk_bf16_f32 v131, v157, v220
	v_cvt_pk_bf16_f32 v132, v156, v218
	v_cvt_pk_bf16_f32 v133, v154, v155
	v_cvt_pk_bf16_f32 v154, v151, v153
	v_mfma_f32_32x32x16_bf16 v[64:79], v[226:229], v[230:233], v[64:79]
	v_cvt_pk_bf16_f32 v155, v150, v152
	v_cvt_pk_bf16_f32 v156, v147, v149
	v_cvt_pk_bf16_f32 v157, v146, v148
	v_cvt_pk_bf16_f32 v218, v142, v143
	v_cvt_pk_bf16_f32 v219, v140, v141
	v_cvt_pk_bf16_f32 v220, v134, v135
	v_cvt_pk_bf16_f32 v221, v191, v205
	v_cvt_pk_bf16_f32 v224, v207, v210
	v_cvt_pk_bf16_f32 v225, v144, v145
	v_cvt_pk_bf16_f32 v226, v138, v139
	v_cvt_pk_bf16_f32 v227, v136, v137
	s_nop 0
	v_permlane32_swap_b32_e32 v222, v223
	v_permlane32_swap_b32_e32 v130, v132
	v_permlane32_swap_b32_e32 v225, v227
	v_permlane32_swap_b32_e32 v131, v133
	v_permlane32_swap_b32_e32 v154, v156
	v_permlane32_swap_b32_e32 v155, v157
	v_permlane32_swap_b32_e32 v218, v220
	v_permlane32_swap_b32_e32 v219, v221
	v_permlane32_swap_b32_e32 v224, v226
	s_cmp_lt_u32 s69, s68
	s_cselect_b32 s14, 0, s68
	s_cselect_b32 s15, s25, s28
	s_lshl_b32 s14, s14, 6
	s_sub_i32 s14, s15, s14
	s_add_i32 s14, s37, s14
	s_ashr_i32 s15, s14, 31
	v_lshl_add_u64 v[134:135], s[14:15], 0, v[174:175]
	v_lshl_add_u64 v[136:137], v[176:177], 0, s[14:15]
	v_lshlrev_b64 v[134:135], 12, v[134:135]
	v_lshlrev_b64 v[136:137], 12, v[136:137]
	v_lshl_add_u64 v[134:135], v[178:179], 0, v[134:135]
	v_lshl_add_u64 v[138:139], v[178:179], 0, v[136:137]
	v_mad_i64_i32 v[142:143], s[20:21], v164, s14, 0
	v_mad_i64_i32 v[146:147], s[20:21], v168, s14, 0
	v_mad_i64_i32 v[150:151], s[14:15], v172, s14, 0
	global_load_dwordx4 v[134:137], v[134:135], off offset:256
	s_nop 0
	global_load_dwordx4 v[138:141], v[138:139], off offset:256
	v_lshl_add_u64 v[142:143], v[142:143], 1, v[162:163]
	v_lshl_add_u64 v[146:147], v[146:147], 1, v[166:167]
	v_lshl_add_u64 v[150:151], v[150:151], 1, v[170:171]
	global_load_dwordx4 v[142:145], v[142:143], off
	s_nop 0
	global_load_dwordx4 v[146:149], v[146:147], off
	s_nop 0
	global_load_dwordx4 v[150:153], v[150:151], off
	ds_read_b64_tr_b16 v[228:229], v200 offset:0
	ds_read_b64_tr_b16 v[230:231], v200 offset:0x800
	ds_read_b64_tr_b16 v[232:233], v200 offset:0x1000
	ds_read_b64_tr_b16 v[234:235], v200 offset:0x1800
	ds_read_b64_tr_b16 v[236:237], v200 offset:0x2000
	ds_read_b64_tr_b16 v[238:239], v200 offset:0x2800
	ds_read_b64_tr_b16 v[240:241], v200 offset:0x3000
	ds_read_b64_tr_b16 v[242:243], v200 offset:0x3800
	s_waitcnt lgkmcnt(0)
	s_nop 0
	v_mfma_f32_32x32x16_bf16 v[48:63], v[130:133], v[228:231], v[48:63]
	ds_read_b64_tr_b16 v[228:229], v200 offset:0x200
	ds_read_b64_tr_b16 v[230:231], v200 offset:0xa00
	v_mfma_f32_32x32x16_bf16 v[48:63], v[154:157], v[232:235], v[48:63]
	ds_read_b64_tr_b16 v[232:233], v200 offset:0x1200
	ds_read_b64_tr_b16 v[234:235], v200 offset:0x1a00
	v_mfma_f32_32x32x16_bf16 v[48:63], v[218:221], v[236:239], v[48:63]
	ds_read_b64_tr_b16 v[236:237], v200 offset:0x2200
	ds_read_b64_tr_b16 v[238:239], v200 offset:0x2a00
	v_mfma_f32_32x32x16_bf16 v[48:63], v[224:227], v[240:243], v[48:63]
	ds_read_b64_tr_b16 v[240:241], v200 offset:0x3200
	ds_read_b64_tr_b16 v[242:243], v200 offset:0x3a00
	s_waitcnt lgkmcnt(6)
	v_mfma_f32_32x32x16_bf16 v[32:47], v[130:133], v[228:231], v[32:47]
	ds_read_b64_tr_b16 v[228:229], v200 offset:0x400
	ds_read_b64_tr_b16 v[230:231], v200 offset:0xc00
	s_waitcnt lgkmcnt(6)
	v_mfma_f32_32x32x16_bf16 v[32:47], v[154:157], v[232:235], v[32:47]
	ds_read_b64_tr_b16 v[232:233], v200 offset:0x1400
	ds_read_b64_tr_b16 v[234:235], v200 offset:0x1c00
	s_waitcnt lgkmcnt(6)
	v_mfma_f32_32x32x16_bf16 v[32:47], v[218:221], v[236:239], v[32:47]
	ds_read_b64_tr_b16 v[236:237], v200 offset:0x2400
	ds_read_b64_tr_b16 v[238:239], v200 offset:0x2c00
	s_waitcnt lgkmcnt(6)
	v_mfma_f32_32x32x16_bf16 v[32:47], v[224:227], v[240:243], v[32:47]
	ds_read_b64_tr_b16 v[240:241], v200 offset:0x3400
	ds_read_b64_tr_b16 v[242:243], v200 offset:0x3c00
	s_waitcnt lgkmcnt(6)
	v_mfma_f32_32x32x16_bf16 v[16:31], v[130:133], v[228:231], v[16:31]
	ds_read_b64_tr_b16 v[228:229], v200 offset:0x600
	ds_read_b64_tr_b16 v[230:231], v200 offset:0xe00
	s_waitcnt lgkmcnt(6)
	v_mfma_f32_32x32x16_bf16 v[16:31], v[154:157], v[232:235], v[16:31]
	ds_read_b64_tr_b16 v[232:233], v200 offset:0x1600
	ds_read_b64_tr_b16 v[234:235], v200 offset:0x1e00
	s_waitcnt lgkmcnt(6)
	v_mfma_f32_32x32x16_bf16 v[16:31], v[218:221], v[236:239], v[16:31]
	ds_read_b64_tr_b16 v[236:237], v200 offset:0x2600
	ds_read_b64_tr_b16 v[238:239], v200 offset:0x2e00
	s_waitcnt lgkmcnt(6)
	v_mfma_f32_32x32x16_bf16 v[16:31], v[224:227], v[240:243], v[16:31]
	ds_read_b64_tr_b16 v[240:241], v200 offset:0x3600
	ds_read_b64_tr_b16 v[242:243], v200 offset:0x3e00
	s_waitcnt lgkmcnt(6)
	v_mfma_f32_32x32x16_bf16 v[0:15], v[130:133], v[228:231], v[0:15]
	v_max_f32_e32 v130, v81, v81
	v_max_f32_e32 v131, v80, v80
	v_max_f32_e32 v130, v131, v130
	v_max3_f32 v130, v130, v82, v83
	v_max3_f32 v130, v130, v84, v85
	v_max3_f32 v130, v130, v86, v87
	v_max3_f32 v130, v130, v88, v89
	v_max3_f32 v130, v130, v90, v91
	v_max3_f32 v130, v130, v92, v93
	s_waitcnt lgkmcnt(4)
	v_mfma_f32_32x32x16_bf16 v[0:15], v[154:157], v[232:235], v[0:15]
	v_max3_f32 v130, v130, v94, v95
	v_max3_f32 v130, v130, v64, v65
	v_max3_f32 v130, v130, v66, v67
	v_max3_f32 v130, v130, v68, v69
	v_max3_f32 v130, v130, v70, v71
	v_max3_f32 v130, v130, v72, v73
	v_max3_f32 v130, v130, v74, v75
	v_max3_f32 v130, v130, v76, v77
	s_waitcnt lgkmcnt(2)
	v_mfma_f32_32x32x16_bf16 v[0:15], v[218:221], v[236:239], v[0:15]
	v_max3_f32 v130, v130, v78, v79
	v_mov_b32_e32 v131, v130
	s_nop 1
	v_permlane32_swap_b32_e32 v130, v131
	v_max_f32_e32 v131, v131, v131
	v_max_f32_e32 v130, v130, v130
	v_max_f32_e32 v130, v130, v131
	v_sub_f32_e32 v131, v130, v204
	v_cmp_ge_f32_e32 vcc, s72, v131
	v_max_f32_e32 v131, v204, v204
	v_max_f32_e32 v130, v131, v130
	s_waitcnt lgkmcnt(0)
	v_mfma_f32_32x32x16_bf16 v[0:15], v[224:227], v[240:243], v[0:15]
	v_sub_f32_e32 v131, v204, v130
	v_mul_f32_e32 v131, 0x3dd53b94, v131
	v_exp_f32_e32 v131, v131
	s_cmp_eq_u64 vcc, exec
	s_cselect_b64 s[14:15], -1, 0
	v_cndmask_b32_e64 v225, v131, 1.0, s[14:15]
	v_cmp_gt_f32_e32 vcc, 1.0, v225
	s_barrier
; #define SBAR() __builtin_amdgcn_sched_barrier(0)
; #define SWRITE(b, i) do { *(bf16x8*)(V_lds + (b) * SHM_V + vst0) = sr_[i].vs0; *(bf16x8*)(V_lds + (b) * SHM_V + vst1) = sr_[i].vs1; \
;     _Pragma("unroll") for (int c_ = 0; c_ < KCH; ++c_) *(bf16x8*)(K_lds + (b) * SHM_K + kwo[c_]) = sr_[i].ks[c_]; } while (0)
; #define RESC(al) do { if (__any((al) < 1.f)) { if (hi == 0) al_l[r32] = (al); asm volatile("s_waitcnt lgkmcnt(0)" ::: "memory"); \
;     _Pragma("unroll") for (int d = 0; d < 4; ++d) _Pragma("unroll") for (int r = 0; r < 16; ++r) o[d][r] *= al_l[crow(r, hi)]; } } while (0)
; __device__ __forceinline__ void partialSM(f32x16& p0, f32x16& p1, float& m_reg, float& mn, float& alpha, const float C, const float thr) {
;     ...
;     const float mnC = -mn * C;
; #pragma unroll
;     for (int r = 0; r < 16; ++r) p0[r] = fmaf(p0[r], C, mnC);
; #pragma unroll
;     for (int r = 0; r < 16; ++r) p1[r] = fmaf(p1[r], C, mnC);
; #pragma unroll
;     for (int r = 0; r < 16; ++r) p0[r] = __builtin_amdgcn_exp2f(p0[r]);
; }
; __device__ __forceinline__ void finishSM(f32x16& p0, f32x16& p1, float alpha, float& l_reg, bf16x8& pa0, bf16x8& pa1, bf16x8& pa2, bf16x8& pa3) {
; #pragma unroll
;     for (int r = 0; r < 16; ++r) p1[r] = __builtin_amdgcn_exp2f(p1[r]);
; template <int DQK, int DK1, int LDQ, int LDK, int LDKR, int LDV, int NQL, int SDEPTH>
; __device__ __forceinline__ void attn_core(const AttnArgs& a, char* lds, f32x16 (&o)[4]) {
;     ...
;         __syncthreads(); SWRITE(0, SE);
;         RESC(alB); __syncthreads();
;         SBAR(); QKT(pA0, pA1, K_lds);
	s_waitcnt vmcnt(4)
	ds_write_b128 v186, v[134:137]
	s_waitcnt vmcnt(3)
	ds_write_b128 v188, v[138:141]
	s_waitcnt vmcnt(2)
	ds_write_b128 v194, v[142:145] offset:32768
	s_waitcnt vmcnt(1)
	ds_write_b128 v196, v[146:149] offset:32768
	s_waitcnt vmcnt(0)
	ds_write_b128 v198, v[150:153] offset:32768
	s_cbranch_vccz .LBB0_223
	s_and_saveexec_b64 s[20:21], s[12:13]
	ds_write_b32 v165, v225 offset:128
	s_or_b64 exec, exec, s[20:21]
	s_waitcnt lgkmcnt(0)
	v_add_u32_e32 v131, v161, v96
	ds_read_b128 v[132:135], v131 offset:224
	ds_read_b128 v[136:139], v131 offset:192
	ds_read_b128 v[140:143], v131 offset:160
	ds_read_b128 v[144:147], v131 offset:128
	s_waitcnt lgkmcnt(3)
	v_pk_mul_f32 v[60:61], v[60:61], v[132:133]
	s_waitcnt lgkmcnt(2)
	v_pk_mul_f32 v[56:57], v[56:57], v[136:137]
	s_waitcnt lgkmcnt(1)
	v_pk_mul_f32 v[52:53], v[52:53], v[140:141]
	v_pk_mul_f32 v[62:63], v[62:63], v[134:135]
	v_pk_mul_f32 v[58:59], v[58:59], v[138:139]
	v_pk_mul_f32 v[54:55], v[54:55], v[142:143]
	s_waitcnt lgkmcnt(0)
	v_pk_mul_f32 v[50:51], v[50:51], v[146:147]
	v_pk_mul_f32 v[48:49], v[48:49], v[144:145]
	v_pk_mul_f32 v[44:45], v[44:45], v[132:133]
	v_pk_mul_f32 v[40:41], v[40:41], v[136:137]
	v_pk_mul_f32 v[36:37], v[36:37], v[140:141]
	v_pk_mul_f32 v[46:47], v[46:47], v[134:135]
	v_pk_mul_f32 v[42:43], v[42:43], v[138:139]
	v_pk_mul_f32 v[38:39], v[38:39], v[142:143]
	v_pk_mul_f32 v[34:35], v[34:35], v[146:147]
	v_pk_mul_f32 v[32:33], v[32:33], v[144:145]
	v_pk_mul_f32 v[28:29], v[28:29], v[132:133]
	v_pk_mul_f32 v[24:25], v[24:25], v[136:137]
	v_pk_mul_f32 v[20:21], v[20:21], v[140:141]
	v_pk_mul_f32 v[30:31], v[30:31], v[134:135]
	v_pk_mul_f32 v[26:27], v[26:27], v[138:139]
	v_pk_mul_f32 v[22:23], v[22:23], v[142:143]
	v_pk_mul_f32 v[18:19], v[18:19], v[146:147]
	v_pk_mul_f32 v[16:17], v[16:17], v[144:145]
	v_pk_mul_f32 v[12:13], v[12:13], v[132:133]
	v_pk_mul_f32 v[8:9], v[8:9], v[136:137]
	v_pk_mul_f32 v[4:5], v[4:5], v[140:141]
	v_pk_mul_f32 v[14:15], v[14:15], v[134:135]
	v_pk_mul_f32 v[10:11], v[10:11], v[138:139]
	v_pk_mul_f32 v[6:7], v[6:7], v[142:143]
	v_pk_mul_f32 v[2:3], v[2:3], v[146:147]
	v_pk_mul_f32 v[0:1], v[0:1], v[144:145]
.LBB0_223:
	v_cndmask_b32_e64 v204, v130, v204, s[14:15]
	v_mul_f32_e32 v138, 0xbdd53b94, v204
	v_fmamk_f32 v80, v80, 0x3dd53b94, v138
	v_fmamk_f32 v140, v70, 0x3dd53b94, v138
	v_fmamk_f32 v70, v87, 0x3dd53b94, v138
	v_exp_f32_e32 v130, v80
	v_exp_f32_e32 v224, v70
	v_fmamk_f32 v82, v82, 0x3dd53b94, v138
	v_fmamk_f32 v84, v84, 0x3dd53b94, v138
	v_fmamk_f32 v86, v86, 0x3dd53b94, v138
	v_fmamk_f32 v88, v88, 0x3dd53b94, v138
	v_fmamk_f32 v90, v90, 0x3dd53b94, v138
	v_fmamk_f32 v92, v92, 0x3dd53b94, v138
	v_fmamk_f32 v94, v94, 0x3dd53b94, v138
	v_fmamk_f32 v145, v64, 0x3dd53b94, v138
	v_fmamk_f32 v144, v66, 0x3dd53b94, v138
	v_fmamk_f32 v143, v68, 0x3dd53b94, v138
	v_fmamk_f32 v139, v72, 0x3dd53b94, v138
	v_fmamk_f32 v146, v74, 0x3dd53b94, v138
	v_fmamk_f32 v142, v76, 0x3dd53b94, v138
	v_fmamk_f32 v141, v78, 0x3dd53b94, v138
	v_fmamk_f32 v64, v81, 0x3dd53b94, v138
	v_fmamk_f32 v66, v83, 0x3dd53b94, v138
	v_fmamk_f32 v68, v85, 0x3dd53b94, v138
	v_fmamk_f32 v72, v89, 0x3dd53b94, v138
	v_fmamk_f32 v74, v91, 0x3dd53b94, v138
	v_fmamk_f32 v76, v93, 0x3dd53b94, v138
	v_fmamk_f32 v78, v95, 0x3dd53b94, v138
	v_exp_f32_e32 v131, v82
	v_exp_f32_e32 v132, v84
	v_exp_f32_e32 v133, v86
	v_exp_f32_e32 v137, v88
	v_exp_f32_e32 v136, v90
	v_exp_f32_e32 v135, v92
	v_exp_f32_e32 v134, v94
	v_fmamk_f32 v147, v65, 0x3dd53b94, v138
	v_fmamk_f32 v156, v67, 0x3dd53b94, v138
	v_fmamk_f32 v157, v69, 0x3dd53b94, v138
	v_fmamk_f32 v191, v71, 0x3dd53b94, v138
	v_fmamk_f32 v205, v73, 0x3dd53b94, v138
	v_fmamk_f32 v207, v75, 0x3dd53b94, v138
	v_fmamk_f32 v210, v77, 0x3dd53b94, v138
	v_fmac_f32_e32 v138, 0x3dd53b94, v79
	v_exp_f32_e32 v211, v64
	v_exp_f32_e32 v212, v66
	v_exp_f32_e32 v213, v68
	v_exp_f32_e32 v228, v72
	v_exp_f32_e32 v229, v74
	v_exp_f32_e32 v230, v76
	v_exp_f32_e32 v231, v78
	s_waitcnt lgkmcnt(0)
	s_barrier
	ds_read_b128 v[64:67], v184 offset:32768
	ds_read_b128 v[68:71], v184 offset:45056
	ds_read_b128 v[148:151], v192 offset:32768
	ds_read_b128 v[152:155], v192 offset:45056
	v_exp_f32_e32 v145, v145
	v_exp_f32_e32 v147, v147
	s_waitcnt lgkmcnt(3)
	v_mfma_f32_32x32x16_bf16 v[80:95], v[64:67], v[126:129], 0
	v_exp_f32_e32 v144, v144
	v_exp_f32_e32 v143, v143
	v_exp_f32_e32 v140, v140
	v_exp_f32_e32 v139, v139
	v_exp_f32_e32 v146, v146
	v_exp_f32_e32 v142, v142
	v_exp_f32_e32 v141, v141
	s_waitcnt lgkmcnt(2)
	v_mfma_f32_32x32x16_bf16 v[64:79], v[68:71], v[126:129], 0
	v_exp_f32_e32 v138, v138
	s_waitcnt lgkmcnt(0)
	v_mfma_f32_32x32x16_bf16 v[64:79], v[152:155], v[122:125], v[64:79]
	v_mfma_f32_32x32x16_bf16 v[80:95], v[148:151], v[122:125], v[80:95]
	ds_read_b128 v[148:151], v190 offset:32768
	ds_read_b128 v[152:155], v190 offset:45056
	s_waitcnt lgkmcnt(0)
	v_mfma_f32_32x32x16_bf16 v[64:79], v[152:155], v[118:121], v[64:79]
	v_mfma_f32_32x32x16_bf16 v[80:95], v[148:151], v[118:121], v[80:95]
	ds_read_b128 v[148:151], v173 offset:32768
	ds_read_b128 v[152:155], v173 offset:45056
	s_waitcnt lgkmcnt(0)
	v_mfma_f32_32x32x16_bf16 v[64:79], v[152:155], v[114:117], v[64:79]
	v_mfma_f32_32x32x16_bf16 v[80:95], v[148:151], v[114:117], v[80:95]
	ds_read_b128 v[148:151], v184 offset:32896
	ds_read_b128 v[152:155], v184 offset:45184
	s_waitcnt lgkmcnt(0)
	v_mfma_f32_32x32x16_bf16 v[64:79], v[152:155], v[110:113], v[64:79]
	v_mfma_f32_32x32x16_bf16 v[80:95], v[148:151], v[110:113], v[80:95]
	ds_read_b128 v[148:151], v192 offset:32896
	ds_read_b128 v[152:155], v192 offset:45184
	s_waitcnt lgkmcnt(0)
; #define SBAR() __builtin_amdgcn_sched_barrier(0)
; #define SLOAD(i, j) do { const long rb_ = KROW(j); sr_[i].vs0 = *(const bf16x8*)(a.V + (rb_ + sr) * LDV + sc); sr_[i].vs1 = *(const bf16x8*)(a.V + (rb_ + 32 + sr) * LDV + sc); \
;     _Pragma("unroll") for (int c_ = 0; c_ < KCH; ++c_) sr_[i].ks[c_] = *(const bf16x8*)(kptr[c_] + rb_ * kld[c_]); } while (0)
; __device__ __forceinline__ void finishSM(f32x16& p0, f32x16& p1, float alpha, float& l_reg, bf16x8& pa0, bf16x8& pa1, bf16x8& pa2, bf16x8& pa3) {
; #pragma unroll
;     for (int r = 0; r < 16; ++r) p1[r] = __builtin_amdgcn_exp2f(p1[r]);
;     float ps = 0;
; #pragma unroll
;     for (int r = 0; r < 16; ++r) ps += p0[r];
; #pragma unroll
;     for (int r = 0; r < 16; ++r) ps += p1[r];
;     { auto rr = __builtin_amdgcn_permlane32_swap(__float_as_uint(ps), __float_as_uint(ps), false, false);
;       ps = __uint_as_float(rr[0]) + __uint_as_float(rr[1]); }
;     l_reg = l_reg * alpha + ps;
;     ...
;     PK4(p0, 0, pa0); PK4(p0, 8, pa1); PK4(p1, 0, pa2); PK4(p1, 8, pa3);
;     ...
; }
; template <int DQK, int DK1, int LDQ, int LDK, int LDKR, int LDV, int NQL, int SDEPTH>
; __device__ __forceinline__ void attn_core(const AttnArgs& a, char* lds, f32x16 (&o)[4]) {
;     ...
;         SBAR(); QKT(pA0, pA1, K_lds);
;         finishSM(pB0, pB1, alB, l_reg, pa0, pa1, pa2, pa3); SBAR();
;         if (SDEPTH == 1 || j + 3 < NT) SLOAD(SE, j + 1 + SDEPTH); SBAR();
	v_mfma_f32_32x32x16_bf16 v[64:79], v[152:155], v[106:109], v[64:79]
	v_mfma_f32_32x32x16_bf16 v[80:95], v[148:151], v[106:109], v[80:95]
	ds_read_b128 v[148:151], v190 offset:32896
	ds_read_b128 v[152:155], v190 offset:45184
	s_waitcnt lgkmcnt(0)
	v_mfma_f32_32x32x16_bf16 v[64:79], v[152:155], v[102:105], v[64:79]
	v_mfma_f32_32x32x16_bf16 v[80:95], v[148:151], v[102:105], v[80:95]
	ds_read_b128 v[148:151], v173 offset:32896
	ds_read_b128 v[152:155], v173 offset:45184
	s_waitcnt lgkmcnt(0)
	v_mfma_f32_32x32x16_bf16 v[64:79], v[152:155], v[98:101], v[64:79]
	v_mfma_f32_32x32x16_bf16 v[80:95], v[148:151], v[98:101], v[80:95]
	ds_read_b128 v[148:151], v184 offset:33024
	ds_read_b128 v[152:155], v184 offset:45312
	ds_read_b128 v[218:221], v181
	s_waitcnt lgkmcnt(0)
	v_mfma_f32_32x32x16_bf16 v[64:79], v[152:155], v[218:221], v[64:79]
	v_mfma_f32_32x32x16_bf16 v[80:95], v[148:151], v[218:221], v[80:95]
	ds_read_b128 v[148:151], v192 offset:33024
	ds_read_b128 v[152:155], v192 offset:45312
	ds_read_b128 v[218:221], v181 offset:8192
	s_waitcnt lgkmcnt(0)
	v_mfma_f32_32x32x16_bf16 v[64:79], v[152:155], v[218:221], v[64:79]
	v_mfma_f32_32x32x16_bf16 v[80:95], v[148:151], v[218:221], v[80:95]
	ds_read_b128 v[148:151], v190 offset:33024
	ds_read_b128 v[152:155], v190 offset:45312
	ds_read_b128 v[218:221], v181 offset:16384
	s_waitcnt lgkmcnt(0)
	v_mfma_f32_32x32x16_bf16 v[64:79], v[152:155], v[218:221], v[64:79]
	v_mfma_f32_32x32x16_bf16 v[80:95], v[148:151], v[218:221], v[80:95]
	ds_read_b128 v[148:151], v173 offset:33024
	ds_read_b128 v[152:155], v173 offset:45312
	ds_read_b128 v[218:221], v181 offset:24576
	s_waitcnt lgkmcnt(0)
	v_mfma_f32_32x32x16_bf16 v[64:79], v[152:155], v[218:221], v[64:79]
	v_add_f32_e32 v154, 0, v130
	v_add_f32_e32 v154, v211, v154
	v_add_f32_e32 v154, v131, v154
	v_add_f32_e32 v154, v212, v154
	v_add_f32_e32 v154, v132, v154
	v_add_f32_e32 v154, v213, v154
	v_add_f32_e32 v154, v133, v154
	v_add_f32_e32 v154, v224, v154
	v_add_f32_e32 v154, v137, v154
	v_add_f32_e32 v154, v228, v154
	v_add_f32_e32 v154, v136, v154
	v_add_f32_e32 v154, v229, v154
	v_add_f32_e32 v154, v135, v154
	v_add_f32_e32 v154, v230, v154
	v_add_f32_e32 v154, v134, v154
	v_mfma_f32_32x32x16_bf16 v[80:95], v[148:151], v[218:221], v[80:95]
	v_exp_f32_e32 v148, v156
	v_add_f32_e32 v154, v231, v154
	v_add_f32_e32 v154, v145, v154
	v_exp_f32_e32 v149, v157
	v_add_f32_e32 v154, v147, v154
	v_add_f32_e32 v154, v144, v154
	v_exp_f32_e32 v150, v191
	v_add_f32_e32 v154, v148, v154
	v_add_f32_e32 v154, v143, v154
	v_exp_f32_e32 v151, v205
	v_add_f32_e32 v154, v149, v154
	v_add_f32_e32 v154, v140, v154
	v_exp_f32_e32 v152, v207
	v_add_f32_e32 v154, v150, v154
	v_add_f32_e32 v154, v139, v154
	v_exp_f32_e32 v153, v210
	v_add_f32_e32 v154, v151, v154
	v_add_f32_e32 v154, v146, v154
	v_add_f32_e32 v154, v152, v154
	v_add_f32_e32 v154, v142, v154
	v_add_f32_e32 v154, v153, v154
	v_add_f32_e32 v154, v141, v154
	v_add_f32_e32 v226, v138, v154
	v_mov_b32_e32 v227, v226
	v_cvt_pk_bf16_f32 v130, v130, v211
	v_cvt_pk_bf16_f32 v131, v131, v212
	v_cvt_pk_bf16_f32 v132, v132, v213
	s_nop 1
	v_permlane32_swap_b32_e32 v226, v227
	v_cvt_pk_bf16_f32 v133, v133, v224
	v_permlane32_swap_b32_e32 v130, v132
	v_cvt_pk_bf16_f32 v154, v137, v228
	v_cvt_pk_bf16_f32 v155, v136, v229
	v_cvt_pk_bf16_f32 v156, v135, v230
	v_cvt_pk_bf16_f32 v157, v134, v231
	v_cvt_pk_bf16_f32 v218, v145, v147
	v_cvt_pk_bf16_f32 v219, v144, v148
	v_cvt_pk_bf16_f32 v220, v143, v149
	v_cvt_pk_bf16_f32 v221, v140, v150
	v_cvt_pk_bf16_f32 v228, v139, v151
	v_cvt_pk_bf16_f32 v229, v146, v152
	v_cvt_pk_bf16_f32 v230, v142, v153
	v_cvt_pk_bf16_f32 v231, v141, v138
	v_permlane32_swap_b32_e32 v131, v133
	v_permlane32_swap_b32_e32 v154, v156
	v_permlane32_swap_b32_e32 v155, v157
	v_permlane32_swap_b32_e32 v218, v220
	v_permlane32_swap_b32_e32 v219, v221
	v_permlane32_swap_b32_e32 v228, v230
	v_permlane32_swap_b32_e32 v229, v231
	s_add_i32 s38, s69, 1
	s_cmp_lt_u32 s38, s68
	s_cselect_b32 s14, 0, s68
	s_cselect_b32 s15, s25, s28
	s_lshl_b32 s14, s14, 6
	s_sub_i32 s14, s15, s14
	s_add_i32 s14, s37, s14
	s_add_i32 s14, s14, 64
	s_ashr_i32 s15, s14, 31
	v_lshl_add_u64 v[134:135], s[14:15], 0, v[174:175]
	v_lshl_add_u64 v[136:137], v[176:177], 0, s[14:15]
	v_lshlrev_b64 v[134:135], 12, v[134:135]
	v_lshlrev_b64 v[136:137], 12, v[136:137]
	v_lshl_add_u64 v[134:135], v[178:179], 0, v[134:135]
	v_lshl_add_u64 v[138:139], v[178:179], 0, v[136:137]
	v_mad_i64_i32 v[142:143], s[20:21], v164, s14, 0
	v_mad_i64_i32 v[146:147], s[20:21], v168, s14, 0
	v_mad_i64_i32 v[150:151], s[14:15], v172, s14, 0
	global_load_dwordx4 v[134:137], v[134:135], off offset:256
	s_nop 0
	global_load_dwordx4 v[138:141], v[138:139], off offset:256
	v_lshl_add_u64 v[142:143], v[142:143], 1, v[162:163]
	v_lshl_add_u64 v[146:147], v[146:147], 1, v[166:167]
	v_lshl_add_u64 v[150:151], v[150:151], 1, v[170:171]
	global_load_dwordx4 v[142:145], v[142:143], off
	s_nop 0
	global_load_dwordx4 v[146:149], v[146:147], off
	s_nop 0
	global_load_dwordx4 v[150:153], v[150:151], off
	ds_read_b64_tr_b16 v[232:233], v169 offset:0
	ds_read_b64_tr_b16 v[234:235], v169 offset:0x800
	ds_read_b64_tr_b16 v[236:237], v169 offset:0x1000
	ds_read_b64_tr_b16 v[238:239], v169 offset:0x1800
	ds_read_b64_tr_b16 v[240:241], v169 offset:0x2000
	ds_read_b64_tr_b16 v[242:243], v169 offset:0x2800
	ds_read_b64_tr_b16 v[244:245], v169 offset:0x3000
	ds_read_b64_tr_b16 v[246:247], v169 offset:0x3800
	s_waitcnt lgkmcnt(0)
; #define SBAR() __builtin_amdgcn_sched_barrier(0)
; template <int OFF> __device__ __forceinline__ s16x4 tr_read(int vb) { s16x4 r; asm volatile("ds_read_b64_tr_b16 %0, %1 offset:%2" : "=&v"(r) : "v"(vb), "i"(OFF) : "memory"); return r; }
; template <int D0> __device__ __forceinline__ void pv_one(f32x16& od, int vb, bf16x8 pa0, bf16x8 pa1, bf16x8 pa2, bf16x8 pa3) {
;     const s16x4 l0 = tr_read<v_rd_off(D0, 0, 0)>(vb), h0 = tr_read<v_rd_off(D0, 0, 1)>(vb), l1 = tr_read<v_rd_off(D0, 1, 0)>(vb), h1 = tr_read<v_rd_off(D0, 1, 1)>(vb);
;     const s16x4 l2 = tr_read<v_rd_off(D0, 2, 0)>(vb), h2 = tr_read<v_rd_off(D0, 2, 1)>(vb), l3 = tr_read<v_rd_off(D0, 3, 0)>(vb), h3 = tr_read<v_rd_off(D0, 3, 1)>(vb);
;     asm volatile("s_waitcnt lgkmcnt(0)" ::: "memory"); SBAR();
;     ...
;     od = __builtin_amdgcn_mfma_f32_32x32x16_bf16(pa0, PK(l0, h0), od, 0, 0, 0);
;     od = __builtin_amdgcn_mfma_f32_32x32x16_bf16(pa1, PK(l1, h1), od, 0, 0, 0);
;     od = __builtin_amdgcn_mfma_f32_32x32x16_bf16(pa2, PK(l2, h2), od, 0, 0, 0);
;     od = __builtin_amdgcn_mfma_f32_32x32x16_bf16(pa3, PK(l3, h3), od, 0, 0, 0);
;     ...
; }
; __device__ __forceinline__ void pv_d0(f32x16* o, int vb, bf16x8 pa0, bf16x8 pa1, bf16x8 pa2, bf16x8 pa3) {
;     pv_one<0>(o[0], vb, pa0, pa1, pa2, pa3); pv_one<1>(o[1], vb, pa0, pa1, pa2, pa3); pv_one<2>(o[2], vb, pa0, pa1, pa2, pa3); pv_one<3>(o[3], vb, pa0, pa1, pa2, pa3);
; }
; __device__ __forceinline__ void partialSM(f32x16& p0, f32x16& p1, float& m_reg, float& mn, float& alpha, const float C, const float thr) {
;     float pmax = p0[0];
; #pragma unroll
;     for (int r = 1; r < 16; ++r) pmax = fmaxf(pmax, p0[r]);
; #pragma unroll
;     for (int r = 0; r < 16; ++r) pmax = fmaxf(pmax, p1[r]);
;     { auto rr = __builtin_amdgcn_permlane32_swap(__float_as_uint(pmax), __float_as_uint(pmax), false, false);
;       pmax = fmaxf(__uint_as_float(rr[0]), __uint_as_float(rr[1])); }
;     if (__builtin_expect(__all(pmax - m_reg <= thr), 1)) { mn = m_reg; alpha = 1.f; }
;     else { mn = fmaxf(m_reg, pmax); alpha = __builtin_amdgcn_exp2f((m_reg - mn) * C); m_reg = mn; }
;     const float mnC = -mn * C;
; #pragma unroll
;     for (int r = 0; r < 16; ++r) p0[r] = fmaf(p0[r], C, mnC);
; #pragma unroll
;     for (int r = 0; r < 16; ++r) p1[r] = fmaf(p1[r], C, mnC);
; #pragma unroll
;     for (int r = 0; r < 16; ++r) p0[r] = __builtin_amdgcn_exp2f(p0[r]);
; }
	s_nop 0
	v_mfma_f32_32x32x16_bf16 v[48:63], v[130:133], v[232:235], v[48:63]
	ds_read_b64_tr_b16 v[232:233], v169 offset:0x200
	ds_read_b64_tr_b16 v[234:235], v169 offset:0xa00
	v_mfma_f32_32x32x16_bf16 v[48:63], v[154:157], v[236:239], v[48:63]
	ds_read_b64_tr_b16 v[236:237], v169 offset:0x1200
	ds_read_b64_tr_b16 v[238:239], v169 offset:0x1a00
	v_mfma_f32_32x32x16_bf16 v[48:63], v[218:221], v[240:243], v[48:63]
	ds_read_b64_tr_b16 v[240:241], v169 offset:0x2200
	ds_read_b64_tr_b16 v[242:243], v169 offset:0x2a00
	v_mfma_f32_32x32x16_bf16 v[48:63], v[228:231], v[244:247], v[48:63]
	ds_read_b64_tr_b16 v[244:245], v169 offset:0x3200
	ds_read_b64_tr_b16 v[246:247], v169 offset:0x3a00
	s_waitcnt lgkmcnt(6)
	v_mfma_f32_32x32x16_bf16 v[32:47], v[130:133], v[232:235], v[32:47]
	ds_read_b64_tr_b16 v[232:233], v169 offset:0x400
	ds_read_b64_tr_b16 v[234:235], v169 offset:0xc00
	s_waitcnt lgkmcnt(6)
	v_mfma_f32_32x32x16_bf16 v[32:47], v[154:157], v[236:239], v[32:47]
	ds_read_b64_tr_b16 v[236:237], v169 offset:0x1400
	ds_read_b64_tr_b16 v[238:239], v169 offset:0x1c00
	s_waitcnt lgkmcnt(6)
	v_mfma_f32_32x32x16_bf16 v[32:47], v[218:221], v[240:243], v[32:47]
	ds_read_b64_tr_b16 v[240:241], v169 offset:0x2400
	ds_read_b64_tr_b16 v[242:243], v169 offset:0x2c00
	s_waitcnt lgkmcnt(6)
	v_mfma_f32_32x32x16_bf16 v[32:47], v[228:231], v[244:247], v[32:47]
	ds_read_b64_tr_b16 v[244:245], v169 offset:0x3400
	ds_read_b64_tr_b16 v[246:247], v169 offset:0x3c00
	s_waitcnt lgkmcnt(6)
	v_mfma_f32_32x32x16_bf16 v[16:31], v[130:133], v[232:235], v[16:31]
	ds_read_b64_tr_b16 v[232:233], v169 offset:0x600
	ds_read_b64_tr_b16 v[234:235], v169 offset:0xe00
	s_waitcnt lgkmcnt(6)
	v_mfma_f32_32x32x16_bf16 v[16:31], v[154:157], v[236:239], v[16:31]
	ds_read_b64_tr_b16 v[236:237], v169 offset:0x1600
	ds_read_b64_tr_b16 v[238:239], v169 offset:0x1e00
	s_waitcnt lgkmcnt(6)
	v_mfma_f32_32x32x16_bf16 v[16:31], v[218:221], v[240:243], v[16:31]
	ds_read_b64_tr_b16 v[240:241], v169 offset:0x2600
	ds_read_b64_tr_b16 v[242:243], v169 offset:0x2e00
	s_waitcnt lgkmcnt(6)
	v_mfma_f32_32x32x16_bf16 v[16:31], v[228:231], v[244:247], v[16:31]
	ds_read_b64_tr_b16 v[244:245], v169 offset:0x3600
	ds_read_b64_tr_b16 v[246:247], v169 offset:0x3e00
	s_waitcnt lgkmcnt(6)
	v_mfma_f32_32x32x16_bf16 v[0:15], v[130:133], v[232:235], v[0:15]
	v_max_f32_e32 v130, v81, v81
	v_max_f32_e32 v131, v80, v80
	v_max_f32_e32 v130, v131, v130
	v_max3_f32 v130, v130, v82, v83
	v_max3_f32 v130, v130, v84, v85
	v_max3_f32 v130, v130, v86, v87
	v_max3_f32 v130, v130, v88, v89
	v_max3_f32 v130, v130, v90, v91
	v_max3_f32 v130, v130, v92, v93
	s_waitcnt lgkmcnt(4)
	v_mfma_f32_32x32x16_bf16 v[0:15], v[154:157], v[236:239], v[0:15]
	v_max3_f32 v130, v130, v94, v95
	v_max3_f32 v130, v130, v64, v65
	v_max3_f32 v130, v130, v66, v67
	v_max3_f32 v130, v130, v68, v69
	v_max3_f32 v130, v130, v70, v71
	v_max3_f32 v130, v130, v72, v73
	v_max3_f32 v130, v130, v74, v75
	v_max3_f32 v130, v130, v76, v77
	s_waitcnt lgkmcnt(2)
	v_mfma_f32_32x32x16_bf16 v[0:15], v[218:221], v[240:243], v[0:15]
	v_max3_f32 v130, v130, v78, v79
	v_mov_b32_e32 v131, v130
	s_nop 1
	v_permlane32_swap_b32_e32 v130, v131
	v_max_f32_e32 v131, v131, v131
	v_max_f32_e32 v130, v130, v130
	v_max_f32_e32 v130, v130, v131
	v_sub_f32_e32 v131, v130, v204
	v_cmp_ge_f32_e32 vcc, s72, v131
	v_max_f32_e32 v131, v204, v204
	v_max_f32_e32 v130, v131, v130
	s_waitcnt lgkmcnt(0)
	v_mfma_f32_32x32x16_bf16 v[0:15], v[228:231], v[244:247], v[0:15]
	v_sub_f32_e32 v131, v204, v130
	v_mul_f32_e32 v131, 0x3dd53b94, v131
	v_exp_f32_e32 v131, v131
	s_cmp_eq_u64 vcc, exec
	s_cselect_b64 s[14:15], -1, 0
	v_cndmask_b32_e64 v224, v131, 1.0, s[14:15]
	v_cmp_gt_f32_e32 vcc, 1.0, v224
	s_barrier
	s_waitcnt vmcnt(4)
	ds_write_b128 v186, v[134:137] offset:16384
	s_waitcnt vmcnt(3)
	ds_write_b128 v188, v[138:141] offset:16384
	s_waitcnt vmcnt(2)
	ds_write_b128 v194, v[142:145] offset:57344
	s_waitcnt vmcnt(1)
	ds_write_b128 v196, v[146:149] offset:57344
	s_waitcnt vmcnt(0)
	ds_write_b128 v198, v[150:153] offset:57344
	s_cbranch_vccz .LBB0_227
	s_and_saveexec_b64 s[20:21], s[12:13]
	ds_write_b32 v165, v224 offset:128
	s_or_b64 exec, exec, s[20:21]
	s_waitcnt lgkmcnt(0)
	v_add_u32_e32 v131, v161, v96
	ds_read_b128 v[132:135], v131 offset:224
	ds_read_b128 v[136:139], v131 offset:192
	ds_read_b128 v[140:143], v131 offset:160
	ds_read_b128 v[144:147], v131 offset:128
	s_waitcnt lgkmcnt(3)
	v_pk_mul_f32 v[60:61], v[60:61], v[132:133]
	s_waitcnt lgkmcnt(2)
	v_pk_mul_f32 v[56:57], v[56:57], v[136:137]
	s_waitcnt lgkmcnt(1)
	v_pk_mul_f32 v[52:53], v[52:53], v[140:141]
	v_pk_mul_f32 v[62:63], v[62:63], v[134:135]
	v_pk_mul_f32 v[58:59], v[58:59], v[138:139]
	v_pk_mul_f32 v[54:55], v[54:55], v[142:143]
	s_waitcnt lgkmcnt(0)
	v_pk_mul_f32 v[50:51], v[50:51], v[146:147]
	v_pk_mul_f32 v[48:49], v[48:49], v[144:145]
	v_pk_mul_f32 v[44:45], v[44:45], v[132:133]
	v_pk_mul_f32 v[40:41], v[40:41], v[136:137]
	v_pk_mul_f32 v[36:37], v[36:37], v[140:141]
	v_pk_mul_f32 v[46:47], v[46:47], v[134:135]
	v_pk_mul_f32 v[42:43], v[42:43], v[138:139]
	v_pk_mul_f32 v[38:39], v[38:39], v[142:143]
	v_pk_mul_f32 v[34:35], v[34:35], v[146:147]
	v_pk_mul_f32 v[32:33], v[32:33], v[144:145]
	v_pk_mul_f32 v[28:29], v[28:29], v[132:133]
	v_pk_mul_f32 v[24:25], v[24:25], v[136:137]
	v_pk_mul_f32 v[20:21], v[20:21], v[140:141]
	v_pk_mul_f32 v[30:31], v[30:31], v[134:135]
	v_pk_mul_f32 v[26:27], v[26:27], v[138:139]
	v_pk_mul_f32 v[22:23], v[22:23], v[142:143]
	v_pk_mul_f32 v[18:19], v[18:19], v[146:147]
	v_pk_mul_f32 v[16:17], v[16:17], v[144:145]
	v_pk_mul_f32 v[12:13], v[12:13], v[132:133]
	v_pk_mul_f32 v[8:9], v[8:9], v[136:137]
	v_pk_mul_f32 v[4:5], v[4:5], v[140:141]
	v_pk_mul_f32 v[14:15], v[14:15], v[134:135]
	v_pk_mul_f32 v[10:11], v[10:11], v[138:139]
	v_pk_mul_f32 v[6:7], v[6:7], v[142:143]
	v_pk_mul_f32 v[2:3], v[2:3], v[146:147]
	v_pk_mul_f32 v[0:1], v[0:1], v[144:145]
